# score loop: MFMAs read the K fragments straight from the two prefetch buffers (no register copies)
# speedup vs baseline: 1.0085x; 1.0085x over previous
; DI f32x16 mfma32(bf16x8 a, bf16x8 b, f32x16 c) { return __builtin_amdgcn_mfma_f32_32x32x16_bf16(a, b, c, 0, 0, 0); }
; DI float half_sum(float v) { auto rr = __builtin_amdgcn_permlane32_swap(__float_as_uint(v), __float_as_uint(v), false, false); return __uint_as_float(rr[0]) + __uint_as_float(rr[1]); }
; DI void selectA_item(const Params& p, int item, int next_item, char* lds, bf16x8 (&qf)[4], float (&wq)[16]) {
;     ...
;     for (int kt = wid; kt < ntile; kt += 8) {
;       if (kt + 8 < ntile) {
; #pragma unroll
;         for (int t = 0; t < 4; ++t) kn[t] = *(const bf16x8*)(Kt + (size_t)(kt + 8) * 2048 + t * 512);
;       }
;       f32x16 s;
; #pragma unroll
;       for (int i = 0; i < 16; ++i) s[i] = 0.f;
; #pragma unroll
;       for (int t = 0; t < 4; ++t) s = mfma32(qf[t], kf[t], s);
;       float v[4];
; #pragma unroll
;       for (int q = 0; q < 4; ++q) {
;         float a = wq[4 * q] * fmaxf(s[4 * q], 0.f);
; #pragma unroll
;         for (int jj = 1; jj < 4; ++jj) a += wq[4 * q + jj] * fmaxf(s[4 * q + jj], 0.f);
;         v[q] = half_sum(a) + 0.f;
;       }
;       const float va = h ? v[2] : v[0], vb = h ? v[3] : v[1];
;       const int key = kt * 32 + r32;
;       sc[(2 * h) * 8192 + key] = va; sc[(2 * h + 1) * 8192 + key] = vb;
;       lo0 = fminf(lo0, va); hi0 = fmaxf(hi0, va); lo1 = fminf(lo1, vb); hi1 = fmaxf(hi1, vb);
; #pragma unroll
;       for (int t = 0; t < 4; ++t) kf[t] = kn[t];
;     }
.Lsc_even_cp:
	v_mfma_f32_32x32x16_bf16 v[136:151], v[32:35], v[20:23], 0
	v_mfma_f32_32x32x16_bf16 v[136:151], v[36:39], v[24:27], v[136:151]
	v_mfma_f32_32x32x16_bf16 v[136:151], v[40:43], v[28:31], v[136:151]
	v_mfma_f32_32x32x16_bf16 v[136:151], v[44:47], v[50:53], v[136:151]
	s_add_i32 s10, s9, 16
	s_cmp_lt_i32 s10, s8
	s_cbranch_scc0 .Lsc_even_nl
	global_load_dwordx4 v[20:23], v[80:81], off offset:-2048
	global_load_dwordx4 v[24:27], v[80:81], off offset:-1024
	global_load_dwordx4 v[28:31], v[80:81], off
	global_load_dwordx4 v[50:53], v[80:81], off offset:1024
	s_mov_b64 s[6:7], 0x8000
	v_lshl_add_u64 v[80:81], v[80:81], 0, s[6:7]
.Lsc_even_nl:
	v_max_f32_e32 v0, 0, v0
	v_max_f32_e32 v1, 0, v1
	v_max_f32_e32 v2, 0, v2
	v_max_f32_e32 v3, 0, v3
	v_max_f32_e32 v4, 0, v4
	v_max_f32_e32 v5, 0, v5
	v_max_f32_e32 v6, 0, v6
	v_max_f32_e32 v7, 0, v7
	v_max_f32_e32 v8, 0, v8
	v_max_f32_e32 v9, 0, v9
	v_max_f32_e32 v10, 0, v10
	v_max_f32_e32 v11, 0, v11
	v_max_f32_e32 v12, 0, v12
	v_max_f32_e32 v13, 0, v13
	v_max_f32_e32 v14, 0, v14
	v_max_f32_e32 v15, 0, v15
	v_mul_f32_e32 v0, v106, v0
	v_mul_f32_e32 v4, v108, v4
	v_mul_f32_e32 v8, v110, v8
	v_mul_f32_e32 v12, v112, v12
	v_fmac_f32_e32 v0, v107, v1
	v_fmac_f32_e32 v4, v109, v5
	v_fmac_f32_e32 v8, v111, v9
	v_fmac_f32_e32 v12, v113, v13
	v_fmac_f32_e32 v0, v104, v2
	v_fmac_f32_e32 v4, v102, v6
	v_fmac_f32_e32 v8, v100, v10
	v_fmac_f32_e32 v12, v98, v14
	v_fmac_f32_e32 v0, v105, v3
	v_fmac_f32_e32 v4, v103, v7
	v_fmac_f32_e32 v8, v101, v11
	v_fmac_f32_e32 v12, v99, v15
	s_nop 1
	v_permlane32_swap_b32_e32 v0, v8
	v_permlane32_swap_b32_e32 v4, v12
	v_add_f32_e32 v0, v0, v8
	v_add_f32_e32 v4, v4, v12
	ds_write2st64_b32 v79, v0, v4 offset1:128
	v_min_f32_e32 v83, v83, v0
	v_max_f32_e32 v73, v73, v0
	v_min_f32_e32 v75, v75, v4
	v_max_f32_e32 v48, v48, v4
	v_add_u32_e32 v79, 0x400, v79

; DI f32x16 mfma32(bf16x8 a, bf16x8 b, f32x16 c) { return __builtin_amdgcn_mfma_f32_32x32x16_bf16(a, b, c, 0, 0, 0); }
; DI float half_sum(float v) { auto rr = __builtin_amdgcn_permlane32_swap(__float_as_uint(v), __float_as_uint(v), false, false); return __uint_as_float(rr[0]) + __uint_as_float(rr[1]); }
; DI void selectA_item(const Params& p, int item, int next_item, char* lds, bf16x8 (&qf)[4], float (&wq)[16]) {
;     ...
;     for (int kt = wid; kt < ntile; kt += 8) {
;       if (kt + 8 < ntile) {
; #pragma unroll
;         for (int t = 0; t < 4; ++t) kn[t] = *(const bf16x8*)(Kt + (size_t)(kt + 8) * 2048 + t * 512);
;       }
;       f32x16 s;
; #pragma unroll
;       for (int i = 0; i < 16; ++i) s[i] = 0.f;
; #pragma unroll
;       for (int t = 0; t < 4; ++t) s = mfma32(qf[t], kf[t], s);
;       float v[4];
; #pragma unroll
;       for (int q = 0; q < 4; ++q) {
;         float a = wq[4 * q] * fmaxf(s[4 * q], 0.f);
; #pragma unroll
;         for (int jj = 1; jj < 4; ++jj) a += wq[4 * q + jj] * fmaxf(s[4 * q + jj], 0.f);
;         v[q] = half_sum(a) + 0.f;
;       }
;       const float va = h ? v[2] : v[0], vb = h ? v[3] : v[1];
;       const int key = kt * 32 + r32;
;       sc[(2 * h) * 8192 + key] = va; sc[(2 * h + 1) * 8192 + key] = vb;
;       lo0 = fminf(lo0, va); hi0 = fmaxf(hi0, va); lo1 = fminf(lo1, vb); hi1 = fmaxf(hi1, vb);
; #pragma unroll
;       for (int t = 0; t < 4; ++t) kf[t] = kn[t];
;     }
.Lsc_odd_cp:
	v_mfma_f32_32x32x16_bf16 v[0:15], v[32:35], v[120:123], 0
	v_mfma_f32_32x32x16_bf16 v[0:15], v[36:39], v[124:127], v[0:15]
	v_mfma_f32_32x32x16_bf16 v[0:15], v[40:43], v[128:131], v[0:15]
	v_mfma_f32_32x32x16_bf16 v[0:15], v[44:47], v[132:135], v[0:15]
	s_add_i32 s10, s9, 16
	s_cmp_lt_i32 s10, s8
	s_cbranch_scc0 .Lsc_odd_nl
	global_load_dwordx4 v[120:123], v[80:81], off offset:-2048
	global_load_dwordx4 v[124:127], v[80:81], off offset:-1024
	global_load_dwordx4 v[128:131], v[80:81], off
	global_load_dwordx4 v[132:135], v[80:81], off offset:1024
	s_mov_b64 s[6:7], 0x8000
	v_lshl_add_u64 v[80:81], v[80:81], 0, s[6:7]
.Lsc_odd_nl:
	v_max_f32_e32 v136, 0, v136
	v_max_f32_e32 v137, 0, v137
	v_max_f32_e32 v138, 0, v138
	v_max_f32_e32 v139, 0, v139
	v_max_f32_e32 v140, 0, v140
	v_max_f32_e32 v141, 0, v141
	v_max_f32_e32 v142, 0, v142
	v_max_f32_e32 v143, 0, v143
	v_max_f32_e32 v144, 0, v144
	v_max_f32_e32 v145, 0, v145
	v_max_f32_e32 v146, 0, v146
	v_max_f32_e32 v147, 0, v147
	v_max_f32_e32 v148, 0, v148
	v_max_f32_e32 v149, 0, v149
	v_max_f32_e32 v150, 0, v150
	v_max_f32_e32 v151, 0, v151
	v_mul_f32_e32 v136, v106, v136
	v_mul_f32_e32 v140, v108, v140
	v_mul_f32_e32 v144, v110, v144
	v_mul_f32_e32 v148, v112, v148
	v_fmac_f32_e32 v136, v107, v137
	v_fmac_f32_e32 v140, v109, v141
	v_fmac_f32_e32 v144, v111, v145
	v_fmac_f32_e32 v148, v113, v149
	v_fmac_f32_e32 v136, v104, v138
	v_fmac_f32_e32 v140, v102, v142
	v_fmac_f32_e32 v144, v100, v146
	v_fmac_f32_e32 v148, v98, v150
	v_fmac_f32_e32 v136, v105, v139
	v_fmac_f32_e32 v140, v103, v143
	v_fmac_f32_e32 v144, v101, v147
	v_fmac_f32_e32 v148, v99, v151
	s_nop 1
	v_permlane32_swap_b32_e32 v136, v144
	v_permlane32_swap_b32_e32 v140, v148
	v_add_f32_e32 v136, v136, v144
	v_add_f32_e32 v140, v140, v148
	ds_write2st64_b32 v79, v136, v140 offset1:128
	v_min_f32_e32 v83, v83, v136
	v_max_f32_e32 v73, v73, v136
	v_min_f32_e32 v75, v75, v140
	v_max_f32_e32 v48, v48, v140
	v_add_u32_e32 v79, 0x400, v79
	s_branch .Lsc_even
